# MoBA step: first item's Q loads issued before the next-block K/V prefetch; that item's first MFMA waits vmcnt(8) (Q only) instead of vmcnt(1)/(0) which also drained the prefetch
# speedup vs baseline: 1.0096x; 1.0096x over previous
; #define MB_LOAD(nn) do { _Pragma("unroll") for (int i = 0; i < 4; ++i) { const int cidx = tid + 512 * i, row = cidx >> 3, ch = cidx & 7; \
;         const bf16* src = Zb + (size_t)((nn) * 256 + row) * ZC + h * 64 + ch * 8; kreg[i] = *(const v4u*)(src + KC); vreg[i] = *(const v4u*)(src + VC); } } while (0)
; #define MB_STORE() do { _Pragma("unroll") for (int i = 0; i < 4; ++i) { const int cidx = tid + 512 * i, row = cidx >> 3, ch = cidx & 7; \
;         *(LAS v4u*)(lds + MB_K + row * 144 + ch * 16) = kreg[i]; *(LAS v4u*)(lds + MB_V + row * 144 + ch * 16) = vreg[i]; } } while (0)
; __device__ __forceinline__ void moba_unit(const Ctx& C, int unit, const float* KM) {
;     ...
;     MB_LOAD(qb);
;     __syncthreads();
;     for (int step = 0; step <= qb; ++step) {
;         __syncthreads();
;         MB_STORE();
;         __syncthreads();
;         if (step < qb) MB_LOAD(step);
.LBB0_487:
	v_add_u32_e32 v32, v206, v213
	s_barrier
	s_waitcnt vmcnt(7)
	ds_write_b128 v32, v[0:3]
	v_add_u32_e32 v32, v207, v213
	s_waitcnt vmcnt(6)
	ds_write_b128 v32, v[4:7]
	v_add_u32_e32 v32, v206, v214
	s_waitcnt vmcnt(5)
	ds_write_b128 v32, v[8:11]
	v_add_u32_e32 v32, v207, v214
	s_waitcnt vmcnt(4)
	ds_write_b128 v32, v[12:15]
	v_add_u32_e32 v32, v206, v215
	s_waitcnt vmcnt(3)
	ds_write_b128 v32, v[16:19]
	v_add_u32_e32 v32, v207, v215
	s_waitcnt vmcnt(2)
	ds_write_b128 v32, v[20:23]
	v_add_u32_e32 v32, v206, v216
	s_waitcnt vmcnt(1)
	ds_write_b128 v32, v[24:27]
	v_add_u32_e32 v32, v207, v216
	s_cmp_ge_i32 s52, s70
	s_waitcnt vmcnt(0)
	ds_write_b128 v32, v[28:31]
	s_waitcnt lgkmcnt(0)
	s_barrier
.LBB0_489:
	v_sub_co_u32_e64 v32, s[20:21], s52, 1
	s_xor_b64 s[48:49], s[20:21], -1
	s_add_i32 s21, s52, s19
	s_lshl_b32 s20, s52, 2
	v_lshlrev_b32_e32 v32, 8, v32
	s_lshl_b32 s21, s21, 10
	s_add_i32 s20, s20, 0
	v_add_u32_e32 v219, 0, v32
	s_sub_i32 s21, 0, s21
	s_mov_b32 s55, 0
	s_mov_b32 s56, s72
	v_mov_b32_e32 v220, v217
	s_branch .LBB0_491
.LBB0_490:
	s_cmp_lg_u32 s55, 0
	s_cbranch_scc1 .LBB0_486
	s_cmp_ge_i32 s52, s70
	s_cbranch_scc1 .LBB0_486
	v_lshl_add_u32 v0, s52, 8, v188
	v_mad_i64_i32 v[0:1], s[22:23], v0, s33, v[104:105]
	v_add_co_u32_e32 v2, vcc, 0x1000, v0
	v_lshl_add_u32 v8, s52, 8, v189
	s_nop 0
	v_addc_co_u32_e32 v3, vcc, 0, v1, vcc
	v_add_co_u32_e32 v4, vcc, 0x2000, v0
	v_mad_i64_i32 v[8:9], s[22:23], v8, s33, v[104:105]
	s_nop 0
	v_addc_co_u32_e32 v5, vcc, 0, v1, vcc
	v_add_co_u32_e32 v10, vcc, 0x1000, v8
	v_lshl_add_u32 v16, s52, 8, v190
	s_nop 0
	v_addc_co_u32_e32 v11, vcc, 0, v9, vcc
	v_add_co_u32_e32 v12, vcc, 0x2000, v8
	v_mad_i64_i32 v[16:17], s[22:23], v16, s33, v[104:105]
	s_nop 0
	v_addc_co_u32_e32 v13, vcc, 0, v9, vcc
	v_add_co_u32_e32 v18, vcc, 0x1000, v16
	v_lshl_add_u32 v24, s52, 8, v191
	s_nop 0
	v_addc_co_u32_e32 v19, vcc, 0, v17, vcc
	v_add_co_u32_e32 v20, vcc, 0x2000, v16
	v_mad_i64_i32 v[24:25], s[22:23], v24, s33, v[104:105]
	s_nop 0
	v_addc_co_u32_e32 v21, vcc, 0, v17, vcc
	v_add_co_u32_e32 v26, vcc, 0x1000, v24
	global_load_dwordx4 v[0:3], v[2:3], off offset:3584
	s_nop 0
	global_load_dwordx4 v[4:7], v[4:5], off offset:512
	v_addc_co_u32_e32 v27, vcc, 0, v25, vcc
	v_add_co_u32_e32 v28, vcc, 0x2000, v24
	global_load_dwordx4 v[8:11], v[10:11], off offset:3584
	s_nop 0
	global_load_dwordx4 v[12:15], v[12:13], off offset:512
	v_addc_co_u32_e32 v29, vcc, 0, v25, vcc
	global_load_dwordx4 v[16:19], v[18:19], off offset:3584
	s_nop 0
	global_load_dwordx4 v[20:23], v[20:21], off offset:512
	s_nop 0
	global_load_dwordx4 v[24:27], v[26:27], off offset:3584
	s_nop 0
	global_load_dwordx4 v[28:31], v[28:29], off offset:512
	s_branch .LBB0_486

; #define LAS __attribute__((address_space(3)))
; #define MB_LOAD(nn) do { _Pragma("unroll") for (int i = 0; i < 4; ++i) { const int cidx = tid + 512 * i, row = cidx >> 3, ch = cidx & 7; \
;         const bf16* src = Zb + (size_t)((nn) * 256 + row) * ZC + h * 64 + ch * 8; kreg[i] = *(const v4u*)(src + KC); vreg[i] = *(const v4u*)(src + VC); } } while (0)
; #define MB_STORE() do { _Pragma("unroll") for (int i = 0; i < 4; ++i) { const int cidx = tid + 512 * i, row = cidx >> 3, ch = cidx & 7; \
;         *(LAS v4u*)(lds + MB_K + row * 144 + ch * 16) = kreg[i]; *(LAS v4u*)(lds + MB_V + row * 144 + ch * 16) = vreg[i]; } } while (0)
; #define MB_QID(st, k, qid, valid) do { if ((st) == 0) { const int it_ = (k) ? 15 - C.wave : C.wave; qid = 16 * it_ + i16; valid = true; } \
;         else { const int pos_ = 16 * (C.wave + 8 * (k)) + i16; valid = pos_ < cnt[(st) - 1]; qid = lists[((st) - 1) * 256 + (valid ? pos_ : 0)]; } } while (0)
; #define MB_QLOAD(qid, d0, d1) do { const bf16* qp_ = Zb + (size_t)(qb * 256 + (qid)) * ZC + QC + h * 64 + 8 * (lane >> 4); d0 = *(const bf16x8*)qp_; d1 = *(const bf16x8*)(qp_ + 32); } while (0)
; template <bool OWN>
; __device__ __forceinline__ void moba_item(const bf16x8 q0, const bf16x8 q1, LAS unsigned char* lds, int lane, int qb, int n, int qid, bool valid, int smax) {
;     ...
;         bf16x8 kf[4][2];
; #pragma unroll
;         for (int t = 0; t < 4; ++t) { const LAS unsigned char* kp = kbase + (64 * sp + 32 * (t >> 1) + 16 * (t & 1)) * 144; kf[t][0] = *(const LAS bf16x8*)kp; kf[t][1] = *(const LAS bf16x8*)(kp + 64); }
; __device__ __forceinline__ void moba_unit(const Ctx& C, int unit, const float* KM) {
;     ...
;     MB_LOAD(qb);
;     __syncthreads();
;     for (int step = 0; step <= qb; ++step) {
;         __syncthreads();
;         MB_STORE();
;         __syncthreads();
;         if (step < qb) MB_LOAD(step);
; #pragma unroll 1
;         for (int k = 0; MB_EXISTS(step, k); ++k) {
;             int cqid; bool cvalid; bf16x8 cq0, cq1;
;             MB_QID(step, k, cqid, cvalid); MB_QLOAD(cqid, cq0, cq1);
.LBB0_500:
	s_waitcnt lgkmcnt(0)
	v_add_u32_e32 v34, s75, v221
	v_mov_b64_e32 v[32:33], s[66:67]
	v_mad_i64_i32 v[32:33], s[22:23], v34, s33, v[32:33]
	v_lshl_add_u64 v[32:33], v[32:33], 0, s[36:37]
	v_lshl_add_u64 v[32:33], v[32:33], 0, v[192:193]
	v_lshl_add_u64 v[34:35], v[32:33], 0, s[88:89]
	v_add_co_u32_e32 v32, vcc, 0x1000, v32
	s_mov_b64 s[42:43], -1
	s_nop 0
	v_addc_co_u32_e32 v33, vcc, 0, v33, vcc
	global_load_dwordx4 v[96:99], v[32:33], off offset:2560
	global_load_dwordx4 v[100:103], v[34:35], off offset:64
	s_cmp_lg_u32 s55, 0
	s_cbranch_scc1 .Lmb_pf_skip_a
	s_cmp_ge_i32 s52, s70
	s_cbranch_scc1 .Lmb_pf_skip_a
	v_lshl_add_u32 v0, s52, 8, v188
	v_mad_i64_i32 v[0:1], s[22:23], v0, s33, v[104:105]
	v_add_co_u32_e32 v2, vcc, 0x1000, v0
	v_lshl_add_u32 v8, s52, 8, v189
	s_nop 0
	v_addc_co_u32_e32 v3, vcc, 0, v1, vcc
	v_add_co_u32_e32 v4, vcc, 0x2000, v0
	v_mad_i64_i32 v[8:9], s[22:23], v8, s33, v[104:105]
	s_nop 0
	v_addc_co_u32_e32 v5, vcc, 0, v1, vcc
	v_add_co_u32_e32 v10, vcc, 0x1000, v8
	v_lshl_add_u32 v16, s52, 8, v190
	s_nop 0
	v_addc_co_u32_e32 v11, vcc, 0, v9, vcc
	v_add_co_u32_e32 v12, vcc, 0x2000, v8
	v_mad_i64_i32 v[16:17], s[22:23], v16, s33, v[104:105]
	s_nop 0
	v_addc_co_u32_e32 v13, vcc, 0, v9, vcc
	v_add_co_u32_e32 v18, vcc, 0x1000, v16
	v_lshl_add_u32 v24, s52, 8, v191
	s_nop 0
	v_addc_co_u32_e32 v19, vcc, 0, v17, vcc
	v_add_co_u32_e32 v20, vcc, 0x2000, v16
	v_mad_i64_i32 v[24:25], s[22:23], v24, s33, v[104:105]
	s_nop 0
	v_addc_co_u32_e32 v21, vcc, 0, v17, vcc
	v_add_co_u32_e32 v26, vcc, 0x1000, v24
	global_load_dwordx4 v[0:3], v[2:3], off offset:3584
	s_nop 0
	global_load_dwordx4 v[4:7], v[4:5], off offset:512
	v_addc_co_u32_e32 v27, vcc, 0, v25, vcc
	v_add_co_u32_e32 v28, vcc, 0x2000, v24
	global_load_dwordx4 v[8:11], v[10:11], off offset:3584
	s_nop 0
	global_load_dwordx4 v[12:15], v[12:13], off offset:512
	v_addc_co_u32_e32 v29, vcc, 0, v25, vcc
	global_load_dwordx4 v[16:19], v[18:19], off offset:3584
	s_nop 0
	global_load_dwordx4 v[20:23], v[20:21], off offset:512
	s_nop 0
	global_load_dwordx4 v[24:27], v[26:27], off offset:3584
	s_nop 0
	global_load_dwordx4 v[28:31], v[28:29], off offset:512
.Lmb_pf_skip_a:
	s_and_b64 vcc, exec, s[48:49]
	v_sub_u32_e32 v222, v221, v208
	s_cbranch_vccz .LBB0_505
	ds_read_b128 v[32:35], v218
	ds_read_b128 v[36:39], v218 offset:64
	ds_read_b128 v[40:43], v218 offset:2304
	ds_read_b128 v[44:47], v218 offset:2368
	ds_read_b128 v[48:51], v218 offset:4608
	ds_read_b128 v[52:55], v218 offset:4672
	ds_read_b128 v[56:59], v218 offset:6912
	ds_read_b128 v[60:63], v218 offset:6976
	s_cmp_lg_u32 s55, 0
	s_cbranch_scc1 .Lmb_w_all
	s_cmp_ge_i32 s52, s70
	s_cbranch_scc1 .Lmb_w_all
	s_waitcnt vmcnt(8)
	s_branch .Lmb_w_done

; #define LAS __attribute__((address_space(3)))
; __device__ __forceinline__ f32x4 mfma16(bf16x8 a, bf16x8 b, f32x4 c) { return __builtin_amdgcn_mfma_f32_16x16x32_bf16(a, b, c, 0, 0, 0); }
; #define SBAR() __builtin_amdgcn_sched_barrier(0)
; #define SBAR() __builtin_amdgcn_sched_barrier(0)
; template <bool OWN>
; __device__ __forceinline__ void moba_item(const bf16x8 q0, const bf16x8 q1, LAS unsigned char* lds, int lane, int qb, int n, int qid, bool valid, int smax) {
;     ...
;     f32x4 S[16];
; #pragma unroll
;     for (int sp = 0; sp < 4; ++sp) if (!OWN || 2 * sp <= smax) {
;         bf16x8 kf[4][2];
; #pragma unroll
;         for (int t = 0; t < 4; ++t) { const LAS unsigned char* kp = kbase + (64 * sp + 32 * (t >> 1) + 16 * (t & 1)) * 144; kf[t][0] = *(const LAS bf16x8*)kp; kf[t][1] = *(const LAS bf16x8*)(kp + 64); }
;         SBAR();
; #pragma unroll
;         for (int t = 0; t < 4; ++t) { f32x4 a = mfma16(kf[t][0], q0, (f32x4){0.f, 0.f, 0.f, 0.f}); S[4 * sp + t] = mfma16(kf[t][1], q1, a); }
;         SBAR();
;     }
;     const float c2 = 0.125f * 1.4426950408889634f;
;     const LAS float* tb = (const LAS float*)(lds + MB_TAB) + (256 * (qb - n) + qid - 4 * g - 255);
;     float mx = NEGF;
; #pragma unroll
;     for (int sp = 0; sp < 4; ++sp) if (!OWN || 2 * sp <= smax) {
;         float tv[16];
; #pragma unroll
;         for (int t = 0; t < 4; ++t)
; #pragma unroll
;             for (int jj = 0; jj < 4; ++jj) tv[4 * t + jj] = tb[255 - (64 * sp + 32 * (t >> 1) + 16 * (t & 1) + jj)];
;         SBAR();
; #pragma unroll
;         for (int t = 0; t < 4; ++t)
; #pragma unroll
;             for (int jj = 0; jj < 4; ++jj) {
;                 float v = S[4 * sp + t][jj] * c2 + tv[4 * t + jj];
;                 if (OWN) { const int key = 64 * sp + 32 * (t >> 1) + 16 * (t & 1) + 4 * g + jj; v = (key <= qid) ? v : NEGF; }
;                 S[4 * sp + t][jj] = v; mx = fmaxf(mx, v);
;             }
;     }
.Lmb_w_done:
	s_waitcnt lgkmcnt(7)
	v_mfma_f32_16x16x32_bf16 v[32:35], v[32:35], v[96:99], 0
	s_waitcnt lgkmcnt(6)
	v_mfma_f32_16x16x32_bf16 v[82:85], v[36:39], v[100:103], v[32:35]
	s_waitcnt lgkmcnt(5)
	v_mfma_f32_16x16x32_bf16 v[32:35], v[40:43], v[96:99], 0
	s_waitcnt lgkmcnt(4)
	v_mfma_f32_16x16x32_bf16 v[86:89], v[44:47], v[100:103], v[32:35]
	s_waitcnt lgkmcnt(3)
	v_mfma_f32_16x16x32_bf16 v[32:35], v[48:51], v[96:99], 0
	s_waitcnt lgkmcnt(2)
	v_mfma_f32_16x16x32_bf16 v[90:93], v[52:55], v[100:103], v[32:35]
	s_waitcnt lgkmcnt(1)
	v_mfma_f32_16x16x32_bf16 v[32:35], v[56:59], v[96:99], 0
	s_waitcnt lgkmcnt(0)
	v_mfma_f32_16x16x32_bf16 v[170:173], v[60:63], v[100:103], v[32:35]
	s_nop 5
	ds_read_b128 v[32:35], v218 offset:9216
	ds_read_b128 v[36:39], v218 offset:9280
	ds_read_b128 v[40:43], v218 offset:11520
	ds_read_b128 v[44:47], v218 offset:11584
	ds_read_b128 v[48:51], v218 offset:13824
	ds_read_b128 v[52:55], v218 offset:13888
	ds_read_b128 v[56:59], v218 offset:16128
	ds_read_b128 v[60:63], v218 offset:16192
	s_waitcnt lgkmcnt(7)
	v_mfma_f32_16x16x32_bf16 v[32:35], v[32:35], v[96:99], 0
	s_waitcnt lgkmcnt(6)
	v_mfma_f32_16x16x32_bf16 v[174:177], v[36:39], v[100:103], v[32:35]
	s_waitcnt lgkmcnt(5)
	v_mfma_f32_16x16x32_bf16 v[32:35], v[40:43], v[96:99], 0
	s_waitcnt lgkmcnt(4)
	v_mfma_f32_16x16x32_bf16 v[178:181], v[44:47], v[100:103], v[32:35]
	s_waitcnt lgkmcnt(3)
	v_mfma_f32_16x16x32_bf16 v[32:35], v[48:51], v[96:99], 0
	s_waitcnt lgkmcnt(2)
	v_mfma_f32_16x16x32_bf16 v[182:185], v[52:55], v[100:103], v[32:35]
	s_waitcnt lgkmcnt(1)
	v_mfma_f32_16x16x32_bf16 v[32:35], v[56:59], v[96:99], 0
	s_waitcnt lgkmcnt(0)
	v_mfma_f32_16x16x32_bf16 v[224:227], v[60:63], v[100:103], v[32:35]
	s_nop 5
	ds_read_b128 v[32:35], v218 offset:18432
	ds_read_b128 v[36:39], v218 offset:18496
	ds_read_b128 v[40:43], v218 offset:20736
	ds_read_b128 v[44:47], v218 offset:20800
	ds_read_b128 v[48:51], v218 offset:23040
	ds_read_b128 v[52:55], v218 offset:23104
	ds_read_b128 v[64:67], v218 offset:25344
	ds_read_b128 v[68:71], v218 offset:25408
	s_waitcnt lgkmcnt(7)
	v_mfma_f32_16x16x32_bf16 v[32:35], v[32:35], v[96:99], 0
	s_waitcnt lgkmcnt(6)
	v_mfma_f32_16x16x32_bf16 v[60:63], v[36:39], v[100:103], v[32:35]
	s_waitcnt lgkmcnt(5)
	v_mfma_f32_16x16x32_bf16 v[32:35], v[40:43], v[96:99], 0
	s_waitcnt lgkmcnt(4)
	v_mfma_f32_16x16x32_bf16 v[56:59], v[44:47], v[100:103], v[32:35]
	s_waitcnt lgkmcnt(3)
	v_mfma_f32_16x16x32_bf16 v[32:35], v[48:51], v[96:99], 0
	s_waitcnt lgkmcnt(2)
	v_mfma_f32_16x16x32_bf16 v[52:55], v[52:55], v[100:103], v[32:35]
	s_waitcnt lgkmcnt(1)
	v_mfma_f32_16x16x32_bf16 v[32:35], v[64:67], v[96:99], 0
	s_waitcnt lgkmcnt(0)
	v_mfma_f32_16x16x32_bf16 v[48:51], v[68:71], v[100:103], v[32:35]
	s_nop 5
	ds_read_b128 v[32:35], v218 offset:27648
	ds_read_b128 v[36:39], v218 offset:27712
	ds_read_b128 v[40:43], v218 offset:29952
	ds_read_b128 v[64:67], v218 offset:30016
	ds_read_b128 v[68:71], v218 offset:32256
	ds_read_b128 v[72:75], v218 offset:32320
	ds_read_b128 v[76:79], v218 offset:34560
	ds_read_b128 v[238:241], v218 offset:34624
	s_waitcnt lgkmcnt(7)
	v_mfma_f32_16x16x32_bf16 v[32:35], v[32:35], v[96:99], 0
	s_waitcnt lgkmcnt(6)
	v_mfma_f32_16x16x32_bf16 v[44:47], v[36:39], v[100:103], v[32:35]
	s_waitcnt lgkmcnt(5)
	v_mfma_f32_16x16x32_bf16 v[32:35], v[40:43], v[96:99], 0
	s_waitcnt lgkmcnt(4)
	v_mfma_f32_16x16x32_bf16 v[40:43], v[64:67], v[100:103], v[32:35]
	s_waitcnt lgkmcnt(3)
	v_mfma_f32_16x16x32_bf16 v[32:35], v[68:71], v[96:99], 0
	s_waitcnt lgkmcnt(2)
	v_mfma_f32_16x16x32_bf16 v[36:39], v[72:75], v[100:103], v[32:35]
	s_waitcnt lgkmcnt(1)
	v_mfma_f32_16x16x32_bf16 v[32:35], v[76:79], v[96:99], 0
	s_waitcnt lgkmcnt(0)
	v_mfma_f32_16x16x32_bf16 v[32:35], v[238:241], v[100:103], v[32:35]
	v_lshl_add_u32 v223, v222, 2, s21
	v_add_u32_e32 v64, 0x5ffc, v223
	v_add_u32_e32 v65, 0x5ff4, v223
	v_add_u32_e32 v66, 0x5fbc, v223
	v_add_u32_e32 v67, 0x5fb4, v223
	ds_read2_b32 v[80:81], v64 offset1:1
	ds_read2_b32 v[76:77], v65 offset1:1
	ds_read2_b32 v[74:75], v66 offset1:1
	ds_read2_b32 v[72:73], v67 offset1:1
	v_add_u32_e32 v64, 0x5f7c, v223
	v_add_u32_e32 v65, 0x5f74, v223
	v_add_u32_e32 v66, 0x5f3c, v223
	v_add_u32_e32 v78, 0x5f34, v223
	ds_read2_b32 v[70:71], v64 offset1:1
	ds_read2_b32 v[68:69], v65 offset1:1
	ds_read2_b32 v[66:67], v66 offset1:1
	ds_read2_b32 v[64:65], v78 offset1:1
	s_waitcnt lgkmcnt(7)
	v_fmamk_f32 v81, v82, 0x3e38aa3b, v81
	v_fmac_f32_e32 v80, 0x3e38aa3b, v83
	v_max3_f32 v78, v81, s17, v80
	s_waitcnt lgkmcnt(6)
	v_fmamk_f32 v77, v84, 0x3e38aa3b, v77
	v_fmac_f32_e32 v76, 0x3e38aa3b, v85
	v_max3_f32 v78, v78, v77, v76
	s_waitcnt lgkmcnt(5)
	v_fmamk_f32 v75, v86, 0x3e38aa3b, v75
	v_fmac_f32_e32 v74, 0x3e38aa3b, v87
	v_max3_f32 v78, v78, v75, v74
	s_waitcnt lgkmcnt(4)
	v_fmamk_f32 v73, v88, 0x3e38aa3b, v73
	v_fmac_f32_e32 v72, 0x3e38aa3b, v89
	v_max3_f32 v78, v78, v73, v72
	s_waitcnt lgkmcnt(3)
	v_fmamk_f32 v71, v90, 0x3e38aa3b, v71
	v_fmac_f32_e32 v70, 0x3e38aa3b, v91
	v_max3_f32 v78, v78, v71, v70
	s_waitcnt lgkmcnt(2)
	v_fmamk_f32 v69, v92, 0x3e38aa3b, v69
	v_fmac_f32_e32 v68, 0x3e38aa3b, v93
	v_max3_f32 v78, v78, v69, v68
	s_waitcnt lgkmcnt(1)
	v_fmamk_f32 v67, v170, 0x3e38aa3b, v67
	v_fmac_f32_e32 v66, 0x3e38aa3b, v171
	v_max3_f32 v78, v78, v67, v66
	s_waitcnt lgkmcnt(0)
; #define SBAR() __builtin_amdgcn_sched_barrier(0)
; #define SBAR() __builtin_amdgcn_sched_barrier(0)
; template <bool OWN>
; __device__ __forceinline__ void moba_item(const bf16x8 q0, const bf16x8 q1, LAS unsigned char* lds, int lane, int qb, int n, int qid, bool valid, int smax) {
;     ...
;     for (int sp = 0; sp < 4; ++sp) if (!OWN || 2 * sp <= smax) {
;         float tv[16];
; #pragma unroll
;         for (int t = 0; t < 4; ++t)
; #pragma unroll
;             for (int jj = 0; jj < 4; ++jj) tv[4 * t + jj] = tb[255 - (64 * sp + 32 * (t >> 1) + 16 * (t & 1) + jj)];
;         SBAR();
; #pragma unroll
;         for (int t = 0; t < 4; ++t)
; #pragma unroll
;             for (int jj = 0; jj < 4; ++jj) {
;                 float v = S[4 * sp + t][jj] * c2 + tv[4 * t + jj];
;                 if (OWN) { const int key = 64 * sp + 32 * (t >> 1) + 16 * (t & 1) + 4 * g + jj; v = (key <= qid) ? v : NEGF; }
;                 S[4 * sp + t][jj] = v; mx = fmaxf(mx, v);
;             }
;     }
;     mx = fmaxf(mx, __shfl_xor(mx, 16)); mx = fmaxf(mx, __shfl_xor(mx, 32));
	v_fmamk_f32 v65, v172, 0x3e38aa3b, v65
	v_fmac_f32_e32 v64, 0x3e38aa3b, v173
	v_max3_f32 v170, v78, v65, v64
	v_add_u32_e32 v78, 0x5efc, v223
	v_add_u32_e32 v90, 0x5e34, v223
	ds_read2_b32 v[92:93], v78 offset1:1
	ds_read2_b32 v[90:91], v90 offset1:1
	v_add_u32_e32 v78, 0x5ef4, v223
	ds_read2_b32 v[88:89], v78 offset1:1
	v_add_u32_e32 v78, 0x5ebc, v223
	ds_read2_b32 v[82:83], v78 offset1:1
	v_add_u32_e32 v78, 0x5eb4, v223
	ds_read2_b32 v[94:95], v78 offset1:1
	v_add_u32_e32 v78, 0x5e7c, v223
	ds_read2_b32 v[86:87], v78 offset1:1
	v_add_u32_e32 v78, 0x5e74, v223
	ds_read2_b32 v[84:85], v78 offset1:1
	v_add_u32_e32 v78, 0x5e3c, v223
	ds_read2_b32 v[78:79], v78 offset1:1
	s_waitcnt lgkmcnt(7)
	v_fmamk_f32 v93, v174, 0x3e38aa3b, v93
	v_fmac_f32_e32 v92, 0x3e38aa3b, v175
	v_max3_f32 v170, v170, v93, v92
	s_waitcnt lgkmcnt(5)
	v_fmamk_f32 v89, v176, 0x3e38aa3b, v89
	v_fmac_f32_e32 v88, 0x3e38aa3b, v177
	v_max3_f32 v170, v170, v89, v88
	s_waitcnt lgkmcnt(4)
	v_fmamk_f32 v83, v178, 0x3e38aa3b, v83
	v_fmac_f32_e32 v82, 0x3e38aa3b, v179
	v_max3_f32 v170, v170, v83, v82
	s_waitcnt lgkmcnt(3)
	v_fmamk_f32 v95, v180, 0x3e38aa3b, v95
	v_fmac_f32_e32 v94, 0x3e38aa3b, v181
	v_max3_f32 v170, v170, v95, v94
	s_waitcnt lgkmcnt(2)
	v_fmamk_f32 v87, v182, 0x3e38aa3b, v87
	v_fmac_f32_e32 v86, 0x3e38aa3b, v183
	v_max3_f32 v170, v170, v87, v86
	s_waitcnt lgkmcnt(1)
	v_fmamk_f32 v85, v184, 0x3e38aa3b, v85
	v_fmac_f32_e32 v84, 0x3e38aa3b, v185
	v_max3_f32 v170, v170, v85, v84
	s_waitcnt lgkmcnt(0)
	v_fmamk_f32 v79, v224, 0x3e38aa3b, v79
	v_fmac_f32_e32 v78, 0x3e38aa3b, v225
	v_max3_f32 v170, v170, v79, v78
	v_fmamk_f32 v91, v226, 0x3e38aa3b, v91
	v_fmac_f32_e32 v90, 0x3e38aa3b, v227
	v_max3_f32 v224, v170, v91, v90
	v_add_u32_e32 v170, 0x5dfc, v223
	v_add_u32_e32 v180, 0x5d34, v223
	ds_read2_b32 v[182:183], v170 offset1:1
	ds_read2_b32 v[180:181], v180 offset1:1
	v_add_u32_e32 v170, 0x5df4, v223
	ds_read2_b32 v[178:179], v170 offset1:1
	v_add_u32_e32 v170, 0x5dbc, v223
	ds_read2_b32 v[172:173], v170 offset1:1
	v_add_u32_e32 v170, 0x5db4, v223
	ds_read2_b32 v[184:185], v170 offset1:1
	v_add_u32_e32 v170, 0x5d7c, v223
	ds_read2_b32 v[176:177], v170 offset1:1
	v_add_u32_e32 v170, 0x5d74, v223
	ds_read2_b32 v[174:175], v170 offset1:1
	v_add_u32_e32 v170, 0x5d3c, v223
	ds_read2_b32 v[170:171], v170 offset1:1
	s_waitcnt lgkmcnt(7)
	v_fmamk_f32 v183, v60, 0x3e38aa3b, v183
	v_fmac_f32_e32 v182, 0x3e38aa3b, v61
	v_max3_f32 v60, v224, v183, v182
	s_waitcnt lgkmcnt(5)
	v_fmamk_f32 v179, v62, 0x3e38aa3b, v179
	v_fmac_f32_e32 v178, 0x3e38aa3b, v63
	v_max3_f32 v60, v60, v179, v178
	s_waitcnt lgkmcnt(4)
	v_fmamk_f32 v173, v56, 0x3e38aa3b, v173
	v_fmac_f32_e32 v172, 0x3e38aa3b, v57
	v_max3_f32 v56, v60, v173, v172
	s_waitcnt lgkmcnt(3)
	v_fmamk_f32 v185, v58, 0x3e38aa3b, v185
	v_fmac_f32_e32 v184, 0x3e38aa3b, v59
	v_max3_f32 v56, v56, v185, v184
	s_waitcnt lgkmcnt(2)
	v_fmamk_f32 v177, v52, 0x3e38aa3b, v177
	v_fmac_f32_e32 v176, 0x3e38aa3b, v53
	v_max3_f32 v52, v56, v177, v176
	s_waitcnt lgkmcnt(1)
	v_fmamk_f32 v175, v54, 0x3e38aa3b, v175
	v_fmac_f32_e32 v174, 0x3e38aa3b, v55
	v_max3_f32 v52, v52, v175, v174
	s_waitcnt lgkmcnt(0)
	v_fmamk_f32 v171, v48, 0x3e38aa3b, v171
	v_fmac_f32_e32 v170, 0x3e38aa3b, v49
	v_max3_f32 v48, v52, v171, v170
	v_fmamk_f32 v181, v50, 0x3e38aa3b, v181
	v_fmac_f32_e32 v180, 0x3e38aa3b, v51
	v_max3_f32 v224, v48, v181, v180
	v_add_u32_e32 v48, 0x5cfc, v223
	v_add_u32_e32 v58, 0x5c34, v223
	ds_read2_b32 v[60:61], v48 offset1:1
	ds_read2_b32 v[58:59], v58 offset1:1
	v_add_u32_e32 v48, 0x5cf4, v223
	ds_read2_b32 v[56:57], v48 offset1:1
	v_add_u32_e32 v48, 0x5cbc, v223
	ds_read2_b32 v[50:51], v48 offset1:1
	v_add_u32_e32 v48, 0x5cb4, v223
	ds_read2_b32 v[62:63], v48 offset1:1
	v_add_u32_e32 v48, 0x5c7c, v223
	ds_read2_b32 v[54:55], v48 offset1:1
	v_add_u32_e32 v48, 0x5c74, v223
	ds_read2_b32 v[52:53], v48 offset1:1
	v_add_u32_e32 v48, 0x5c3c, v223
	ds_read2_b32 v[48:49], v48 offset1:1
	s_waitcnt lgkmcnt(7)
	v_fmamk_f32 v44, v44, 0x3e38aa3b, v61
	v_fmac_f32_e32 v60, 0x3e38aa3b, v45
	v_max3_f32 v45, v224, v44, v60
	s_waitcnt lgkmcnt(5)
	v_fmamk_f32 v46, v46, 0x3e38aa3b, v57
	v_fmac_f32_e32 v56, 0x3e38aa3b, v47
	v_max3_f32 v45, v45, v46, v56
	s_waitcnt lgkmcnt(4)
	v_fmamk_f32 v40, v40, 0x3e38aa3b, v51
	v_fmac_f32_e32 v50, 0x3e38aa3b, v41
	v_max3_f32 v41, v45, v40, v50
	s_waitcnt lgkmcnt(3)
	v_fmamk_f32 v42, v42, 0x3e38aa3b, v63
	v_fmac_f32_e32 v62, 0x3e38aa3b, v43
	v_max3_f32 v41, v41, v42, v62
	s_waitcnt lgkmcnt(2)
	v_fmamk_f32 v36, v36, 0x3e38aa3b, v55
	v_fmac_f32_e32 v54, 0x3e38aa3b, v37
	v_max3_f32 v37, v41, v36, v54
	s_waitcnt lgkmcnt(1)
	v_fmamk_f32 v38, v38, 0x3e38aa3b, v53
	v_fmac_f32_e32 v52, 0x3e38aa3b, v39
	v_max3_f32 v37, v37, v38, v52
	s_waitcnt lgkmcnt(0)
	v_fmamk_f32 v32, v32, 0x3e38aa3b, v49
	v_fmac_f32_e32 v48, 0x3e38aa3b, v33
	v_max3_f32 v33, v37, v32, v48
	v_and_b32_e32 v37, 64, v228
	v_fmac_f32_e32 v58, 0x3e38aa3b, v35
	v_xor_b32_e32 v35, 16, v228
	v_add_u32_e32 v37, 64, v37
	v_cmp_lt_i32_e32 vcc, v35, v37
	v_fmamk_f32 v34, v34, 0x3e38aa3b, v59
	v_max3_f32 v33, v33, v34, v58
	v_cndmask_b32_e32 v35, v228, v35, vcc
	v_lshlrev_b32_e32 v35, 2, v35
	ds_bpermute_b32 v39, v35, v33
	s_waitcnt lgkmcnt(0)
	v_max_f32_e32 v39, v39, v39
	v_max_f32_e32 v33, v33, v39
	v_xor_b32_e32 v39, 32, v228
	v_cmp_lt_i32_e32 vcc, v39, v37
	s_nop 1
	v_cndmask_b32_e32 v37, v228, v39, vcc
	v_lshlrev_b32_e32 v37, 2, v37
	ds_bpermute_b32 v39, v37, v33
	s_waitcnt lgkmcnt(0)
; #define LAS __attribute__((address_space(3)))
; __device__ __forceinline__ unsigned pk2(float lo, float hi) { f32x2_t v = {lo, hi}; bf16x2_t b = __builtin_convertvector(v, bf16x2_t); return __builtin_bit_cast(unsigned, b); }
; __device__ __forceinline__ s16x4 vtr(const LAS unsigned char* p) { return __builtin_bit_cast(s16x4, __builtin_amdgcn_ds_read_tr16_b64_v4i16((LAS s16x4*)p)); }
; template <bool OWN>
; __device__ __forceinline__ void moba_item(const bf16x8 q0, const bf16x8 q1, LAS unsigned char* lds, int lane, int qb, int n, int qid, bool valid, int smax) {
;     ...
;     float sum = 0.f;
; #pragma unroll
;     for (int sp = 0; sp < 4; ++sp) if (!OWN || 2 * sp <= smax) {
; #pragma unroll
;         for (int t = 0; t < 4; ++t)
; #pragma unroll
;             for (int jj = 0; jj < 4; ++jj) { const float pv = __builtin_amdgcn_exp2f(S[4 * sp + t][jj] - mx); S[4 * sp + t][jj] = pv; sum += pv; }
;     }
;     sum += __shfl_xor(sum, 16); sum += __shfl_xor(sum, 32);
;     f32x4 O[4];
; #pragma unroll
;     for (int c = 0; c < 4; ++c) O[c] = (f32x4){0.f, 0.f, 0.f, 0.f};
; #pragma unroll
;     for (int s8 = 0; s8 < 8; ++s8) if (!OWN || (s8 >> 1) * 2 <= smax) {
;         s16x4 vl[4][2];
; #pragma unroll
;         for (int c = 0; c < 4; ++c) { const LAS unsigned char* vp = vbase + (32 * s8) * 144 + 32 * c; vl[c][0] = vtr(vp); vl[c][1] = vtr(vp + 16 * 144); }
;         const int t0 = 2 * s8; v4u pw; pw.x = pk2(S[t0][0], S[t0][1]); pw.y = pk2(S[t0][2], S[t0][3]); pw.z = pk2(S[t0 + 1][0], S[t0 + 1][1]); pw.w = pk2(S[t0 + 1][2], S[t0 + 1][3]);
	v_max_f32_e32 v39, v39, v39
	v_max_f32_e32 v51, v33, v39
	v_sub_f32_e32 v33, v81, v51
	v_exp_f32_e32 v49, v33
	v_sub_f32_e32 v33, v80, v51
	v_exp_f32_e32 v55, v33
	v_sub_f32_e32 v33, v77, v51
	v_exp_f32_e32 v57, v33
	v_sub_f32_e32 v33, v76, v51
	v_exp_f32_e32 v59, v33
	v_sub_f32_e32 v39, v75, v51
	v_add_f32_e32 v33, 0, v49
	v_exp_f32_e32 v61, v39
	v_sub_f32_e32 v39, v74, v51
	v_add_f32_e32 v33, v55, v33
	v_exp_f32_e32 v63, v39
	v_sub_f32_e32 v39, v73, v51
	v_add_f32_e32 v33, v57, v33
	v_exp_f32_e32 v73, v39
	v_sub_f32_e32 v39, v72, v51
	v_add_f32_e32 v33, v59, v33
	v_exp_f32_e32 v72, v39
	v_sub_f32_e32 v39, v71, v51
	v_add_f32_e32 v33, v61, v33
	v_exp_f32_e32 v71, v39
	v_sub_f32_e32 v39, v70, v51
	v_add_f32_e32 v33, v63, v33
	v_exp_f32_e32 v70, v39
	v_sub_f32_e32 v39, v69, v51
	v_add_f32_e32 v33, v73, v33
	v_exp_f32_e32 v74, v39
	v_sub_f32_e32 v39, v68, v51
	v_add_f32_e32 v33, v72, v33
	v_exp_f32_e32 v75, v39
	v_sub_f32_e32 v39, v67, v51
	v_add_f32_e32 v33, v71, v33
	v_exp_f32_e32 v76, v39
	v_sub_f32_e32 v39, v66, v51
	v_add_f32_e32 v33, v70, v33
	v_exp_f32_e32 v77, v39
	v_sub_f32_e32 v39, v65, v51
	v_add_f32_e32 v33, v74, v33
	v_exp_f32_e32 v80, v39
	v_sub_f32_e32 v39, v64, v51
	v_add_f32_e32 v33, v75, v33
	v_exp_f32_e32 v81, v39
	v_sub_f32_e32 v39, v93, v51
	v_add_f32_e32 v33, v76, v33
	v_exp_f32_e32 v93, v39
	v_sub_f32_e32 v39, v92, v51
	v_add_f32_e32 v33, v77, v33
	v_exp_f32_e32 v92, v39
	v_sub_f32_e32 v39, v89, v51
	v_add_f32_e32 v33, v80, v33
	v_exp_f32_e32 v89, v39
	v_sub_f32_e32 v39, v88, v51
	v_add_f32_e32 v33, v81, v33
	v_exp_f32_e32 v88, v39
	v_sub_f32_e32 v39, v83, v51
	v_add_f32_e32 v33, v93, v33
	v_exp_f32_e32 v83, v39
	v_sub_f32_e32 v39, v82, v51
	v_add_f32_e32 v33, v92, v33
	v_exp_f32_e32 v82, v39
	v_sub_f32_e32 v39, v95, v51
	v_add_f32_e32 v33, v89, v33
	v_exp_f32_e32 v95, v39
	v_sub_f32_e32 v39, v94, v51
	v_add_f32_e32 v33, v88, v33
	v_exp_f32_e32 v94, v39
	v_sub_f32_e32 v39, v87, v51
	v_add_f32_e32 v33, v83, v33
	v_exp_f32_e32 v87, v39
	v_sub_f32_e32 v39, v86, v51
	v_add_f32_e32 v33, v82, v33
	v_exp_f32_e32 v86, v39
	v_sub_f32_e32 v39, v85, v51
	v_add_f32_e32 v33, v95, v33
	v_exp_f32_e32 v85, v39
	v_sub_f32_e32 v39, v84, v51
	v_add_f32_e32 v33, v94, v33
	v_exp_f32_e32 v84, v39
	v_sub_f32_e32 v39, v79, v51
	v_add_f32_e32 v33, v87, v33
	v_exp_f32_e32 v79, v39
	v_sub_f32_e32 v39, v78, v51
	v_add_f32_e32 v33, v86, v33
	v_exp_f32_e32 v78, v39
	v_sub_f32_e32 v39, v91, v51
	v_add_f32_e32 v33, v85, v33
	v_exp_f32_e32 v91, v39
	v_sub_f32_e32 v39, v90, v51
	v_add_f32_e32 v33, v84, v33
	v_exp_f32_e32 v90, v39
	v_sub_f32_e32 v39, v183, v51
	v_add_f32_e32 v33, v79, v33
	v_exp_f32_e32 v183, v39
	v_sub_f32_e32 v39, v182, v51
	v_add_f32_e32 v33, v78, v33
	v_exp_f32_e32 v182, v39
	v_sub_f32_e32 v39, v179, v51
	v_add_f32_e32 v33, v91, v33
	v_exp_f32_e32 v179, v39
	v_sub_f32_e32 v39, v178, v51
	v_add_f32_e32 v33, v90, v33
	v_exp_f32_e32 v178, v39
	v_sub_f32_e32 v39, v173, v51
	v_add_f32_e32 v33, v183, v33
	v_exp_f32_e32 v173, v39
	v_sub_f32_e32 v39, v172, v51
	v_add_f32_e32 v33, v182, v33
	v_exp_f32_e32 v172, v39
	v_sub_f32_e32 v39, v185, v51
	v_add_f32_e32 v33, v179, v33
	v_exp_f32_e32 v185, v39
	v_sub_f32_e32 v39, v184, v51
	v_add_f32_e32 v33, v178, v33
	v_exp_f32_e32 v184, v39
	v_sub_f32_e32 v39, v177, v51
	v_add_f32_e32 v33, v173, v33
	v_exp_f32_e32 v177, v39
	v_sub_f32_e32 v39, v176, v51
	v_add_f32_e32 v33, v172, v33
	v_exp_f32_e32 v176, v39
	v_sub_f32_e32 v39, v175, v51
	v_add_f32_e32 v33, v185, v33
	v_exp_f32_e32 v175, v39
	v_sub_f32_e32 v39, v174, v51
	v_add_f32_e32 v33, v184, v33
	v_exp_f32_e32 v174, v39
	v_sub_f32_e32 v39, v171, v51
	v_add_f32_e32 v33, v177, v33
	v_exp_f32_e32 v171, v39
	v_sub_f32_e32 v39, v170, v51
	v_add_f32_e32 v33, v176, v33
	v_exp_f32_e32 v170, v39
	v_sub_f32_e32 v39, v181, v51
	v_add_f32_e32 v33, v175, v33
	v_exp_f32_e32 v181, v39
	v_sub_f32_e32 v39, v180, v51
	v_add_f32_e32 v33, v174, v33
	v_exp_f32_e32 v180, v39
	v_sub_f32_e32 v39, v44, v51
	v_add_f32_e32 v33, v171, v33
	v_exp_f32_e32 v223, v39
	v_sub_f32_e32 v39, v60, v51
	v_add_f32_e32 v33, v170, v33
	v_exp_f32_e32 v224, v39
	v_sub_f32_e32 v39, v46, v51
	v_add_f32_e32 v33, v181, v33
	v_exp_f32_e32 v225, v39
	v_sub_f32_e32 v39, v56, v51
	v_add_f32_e32 v33, v180, v33
	v_exp_f32_e32 v226, v39
	v_sub_f32_e32 v39, v40, v51
	v_add_f32_e32 v33, v223, v33
	v_exp_f32_e32 v227, v39
	v_sub_f32_e32 v39, v50, v51
	v_add_f32_e32 v33, v224, v33
	v_exp_f32_e32 v50, v39
	v_sub_f32_e32 v39, v42, v51
	v_add_f32_e32 v33, v225, v33
	v_exp_f32_e32 v238, v39
	v_sub_f32_e32 v39, v62, v51
	v_add_f32_e32 v33, v226, v33
	v_exp_f32_e32 v239, v39
	v_sub_f32_e32 v36, v36, v51
	v_add_f32_e32 v33, v227, v33
	v_exp_f32_e32 v240, v36
	v_sub_f32_e32 v36, v54, v51
	v_add_f32_e32 v33, v50, v33
	v_exp_f32_e32 v241, v36
	v_sub_f32_e32 v36, v38, v51
	v_add_f32_e32 v33, v238, v33
	v_exp_f32_e32 v242, v36
	v_sub_f32_e32 v36, v52, v51
	v_add_f32_e32 v33, v239, v33
	v_exp_f32_e32 v243, v36
	v_sub_f32_e32 v32, v32, v51
	v_add_f32_e32 v33, v240, v33
	v_exp_f32_e32 v244, v32
	v_sub_f32_e32 v32, v48, v51
	v_add_f32_e32 v33, v241, v33
	v_exp_f32_e32 v48, v32
	v_sub_f32_e32 v32, v34, v51
	v_add_f32_e32 v33, v242, v33
	v_exp_f32_e32 v245, v32
	v_sub_f32_e32 v32, v58, v51
	v_add_f32_e32 v33, v243, v33
	v_exp_f32_e32 v246, v32
	v_add_f32_e32 v32, v244, v33
	v_add_f32_e32 v32, v48, v32
	v_add_f32_e32 v32, v245, v32
	v_add_f32_e32 v32, v246, v32
	ds_bpermute_b32 v33, v35, v32
	v_cvt_pk_bf16_f32 v54, v49, v55
	v_cvt_pk_bf16_f32 v55, v57, v59
	v_cvt_pk_bf16_f32 v56, v61, v63
	v_cvt_pk_bf16_f32 v57, v73, v72
	s_waitcnt lgkmcnt(0)
; #define LAS __attribute__((address_space(3)))
; __device__ __forceinline__ unsigned pk2(float lo, float hi) { f32x2_t v = {lo, hi}; bf16x2_t b = __builtin_convertvector(v, bf16x2_t); return __builtin_bit_cast(unsigned, b); }
; __device__ __forceinline__ f32x4 mfma16(bf16x8 a, bf16x8 b, f32x4 c) { return __builtin_amdgcn_mfma_f32_16x16x32_bf16(a, b, c, 0, 0, 0); }
; __device__ __forceinline__ s16x4 vtr(const LAS unsigned char* p) { return __builtin_bit_cast(s16x4, __builtin_amdgcn_ds_read_tr16_b64_v4i16((LAS s16x4*)p)); }
; #define SBAR() __builtin_amdgcn_sched_barrier(0)
; #define SBAR() __builtin_amdgcn_sched_barrier(0)
; template <bool OWN>
; __device__ __forceinline__ void moba_item(const bf16x8 q0, const bf16x8 q1, LAS unsigned char* lds, int lane, int qb, int n, int qid, bool valid, int smax) {
;     ...
;     f32x4 O[4];
; #pragma unroll
;     for (int c = 0; c < 4; ++c) O[c] = (f32x4){0.f, 0.f, 0.f, 0.f};
; #pragma unroll
;     for (int s8 = 0; s8 < 8; ++s8) if (!OWN || (s8 >> 1) * 2 <= smax) {
;         s16x4 vl[4][2];
; #pragma unroll
;         for (int c = 0; c < 4; ++c) { const LAS unsigned char* vp = vbase + (32 * s8) * 144 + 32 * c; vl[c][0] = vtr(vp); vl[c][1] = vtr(vp + 16 * 144); }
;         const int t0 = 2 * s8; v4u pw; pw.x = pk2(S[t0][0], S[t0][1]); pw.y = pk2(S[t0][2], S[t0][3]); pw.z = pk2(S[t0 + 1][0], S[t0 + 1][1]); pw.w = pk2(S[t0 + 1][2], S[t0 + 1][3]);
;         const bf16x8 pb = __builtin_bit_cast(bf16x8, pw);
;         SBAR();
; #pragma unroll
;         for (int c = 0; c < 4; ++c) { const s16x4 lo = vl[c][0], hi = vl[c][1];
;             const bf16x8 vf = (bf16x8){lo[0], lo[1], lo[2], lo[3], hi[0], hi[1], hi[2], hi[3]};
;             O[c] = mfma16(vf, pb, O[c]); }
;         SBAR();
;     }
;     if (valid) {
	v_add_f32_e32 v52, v32, v33
	ds_bpermute_b32 v53, v37, v52
	ds_read_b64_tr_b16 v[32:33], v209
	ds_read_b64_tr_b16 v[36:37], v209 offset:32
	ds_read_b64_tr_b16 v[40:41], v209 offset:64
	ds_read_b64_tr_b16 v[44:45], v209 offset:96
	ds_read_b64_tr_b16 v[34:35], v209 offset:2304
	ds_read_b64_tr_b16 v[38:39], v209 offset:2336
	ds_read_b64_tr_b16 v[42:43], v209 offset:2368
	ds_read_b64_tr_b16 v[46:47], v209 offset:2400
	s_waitcnt lgkmcnt(3)
	v_mfma_f32_16x16x32_bf16 v[32:35], v[32:35], v[54:57], 0
	s_waitcnt lgkmcnt(2)
	v_mfma_f32_16x16x32_bf16 v[36:39], v[36:39], v[54:57], 0
	s_waitcnt lgkmcnt(1)
	v_mfma_f32_16x16x32_bf16 v[40:43], v[40:43], v[54:57], 0
	s_waitcnt lgkmcnt(0)
	v_mfma_f32_16x16x32_bf16 v[44:47], v[44:47], v[54:57], 0
	ds_read_b64_tr_b16 v[54:55], v209 offset:4608
	ds_read_b64_tr_b16 v[58:59], v209 offset:4640
	ds_read_b64_tr_b16 v[62:63], v209 offset:4672
	ds_read_b64_tr_b16 v[66:67], v209 offset:4704
	ds_read_b64_tr_b16 v[56:57], v209 offset:6912
	ds_read_b64_tr_b16 v[60:61], v209 offset:6944
	ds_read_b64_tr_b16 v[64:65], v209 offset:6976
	ds_read_b64_tr_b16 v[68:69], v209 offset:7008
	v_cvt_pk_bf16_f32 v70, v71, v70
	v_cvt_pk_bf16_f32 v71, v74, v75
	v_cvt_pk_bf16_f32 v72, v76, v77
	v_cvt_pk_bf16_f32 v73, v80, v81
	s_waitcnt lgkmcnt(3)
	s_nop 0
	v_mfma_f32_16x16x32_bf16 v[32:35], v[54:57], v[70:73], v[32:35]
	s_waitcnt lgkmcnt(2)
	v_mfma_f32_16x16x32_bf16 v[36:39], v[58:61], v[70:73], v[36:39]
	s_waitcnt lgkmcnt(1)
	v_mfma_f32_16x16x32_bf16 v[40:43], v[62:65], v[70:73], v[40:43]
	s_waitcnt lgkmcnt(0)
	v_mfma_f32_16x16x32_bf16 v[44:47], v[66:69], v[70:73], v[44:47]
	ds_read_b64_tr_b16 v[54:55], v209 offset:9216
	ds_read_b64_tr_b16 v[58:59], v209 offset:9248
	ds_read_b64_tr_b16 v[62:63], v209 offset:9280
	ds_read_b64_tr_b16 v[66:67], v209 offset:9312
	ds_read_b64_tr_b16 v[56:57], v209 offset:11520
	ds_read_b64_tr_b16 v[60:61], v209 offset:11552
	ds_read_b64_tr_b16 v[64:65], v209 offset:11584
	ds_read_b64_tr_b16 v[68:69], v209 offset:11616
	v_cvt_pk_bf16_f32 v70, v93, v92
	v_cvt_pk_bf16_f32 v71, v89, v88
	v_cvt_pk_bf16_f32 v72, v83, v82
	v_cvt_pk_bf16_f32 v73, v95, v94
	s_waitcnt lgkmcnt(3)
	s_nop 0
	v_mfma_f32_16x16x32_bf16 v[32:35], v[54:57], v[70:73], v[32:35]
	s_waitcnt lgkmcnt(2)
	v_mfma_f32_16x16x32_bf16 v[36:39], v[58:61], v[70:73], v[36:39]
	s_waitcnt lgkmcnt(1)
	v_mfma_f32_16x16x32_bf16 v[40:43], v[62:65], v[70:73], v[40:43]
	s_waitcnt lgkmcnt(0)
	v_mfma_f32_16x16x32_bf16 v[44:47], v[66:69], v[70:73], v[44:47]
	ds_read_b64_tr_b16 v[54:55], v209 offset:13824
	ds_read_b64_tr_b16 v[58:59], v209 offset:13856
	ds_read_b64_tr_b16 v[62:63], v209 offset:13888
	ds_read_b64_tr_b16 v[66:67], v209 offset:13920
	ds_read_b64_tr_b16 v[56:57], v209 offset:16128
	ds_read_b64_tr_b16 v[60:61], v209 offset:16160
	ds_read_b64_tr_b16 v[64:65], v209 offset:16192
	ds_read_b64_tr_b16 v[68:69], v209 offset:16224
	v_cvt_pk_bf16_f32 v70, v87, v86
	v_cvt_pk_bf16_f32 v71, v85, v84
	v_cvt_pk_bf16_f32 v72, v79, v78
	v_cvt_pk_bf16_f32 v73, v91, v90
	s_waitcnt lgkmcnt(3)
	s_nop 0
	v_mfma_f32_16x16x32_bf16 v[32:35], v[54:57], v[70:73], v[32:35]
	s_waitcnt lgkmcnt(2)
	v_mfma_f32_16x16x32_bf16 v[36:39], v[58:61], v[70:73], v[36:39]
	s_waitcnt lgkmcnt(1)
	v_mfma_f32_16x16x32_bf16 v[40:43], v[62:65], v[70:73], v[40:43]
	s_waitcnt lgkmcnt(0)
	v_mfma_f32_16x16x32_bf16 v[44:47], v[66:69], v[70:73], v[44:47]
	ds_read_b64_tr_b16 v[54:55], v209 offset:18432
	ds_read_b64_tr_b16 v[58:59], v209 offset:18464
	ds_read_b64_tr_b16 v[62:63], v209 offset:18496
	ds_read_b64_tr_b16 v[66:67], v209 offset:18528
	ds_read_b64_tr_b16 v[56:57], v209 offset:20736
	ds_read_b64_tr_b16 v[60:61], v209 offset:20768
	ds_read_b64_tr_b16 v[64:65], v209 offset:20800
	ds_read_b64_tr_b16 v[68:69], v209 offset:20832
	v_cvt_pk_bf16_f32 v70, v183, v182
	v_cvt_pk_bf16_f32 v71, v179, v178
	v_cvt_pk_bf16_f32 v72, v173, v172
	v_cvt_pk_bf16_f32 v73, v185, v184
	s_waitcnt lgkmcnt(3)
	s_nop 0
	v_mfma_f32_16x16x32_bf16 v[32:35], v[54:57], v[70:73], v[32:35]
	s_waitcnt lgkmcnt(2)
	v_mfma_f32_16x16x32_bf16 v[36:39], v[58:61], v[70:73], v[36:39]
	s_waitcnt lgkmcnt(1)
	v_mfma_f32_16x16x32_bf16 v[40:43], v[62:65], v[70:73], v[40:43]
	s_waitcnt lgkmcnt(0)
	v_mfma_f32_16x16x32_bf16 v[44:47], v[66:69], v[70:73], v[44:47]
	ds_read_b64_tr_b16 v[54:55], v209 offset:23040
	ds_read_b64_tr_b16 v[58:59], v209 offset:23072
	ds_read_b64_tr_b16 v[62:63], v209 offset:23104
	ds_read_b64_tr_b16 v[66:67], v209 offset:23136
	ds_read_b64_tr_b16 v[56:57], v209 offset:25344
	ds_read_b64_tr_b16 v[60:61], v209 offset:25376
	ds_read_b64_tr_b16 v[64:65], v209 offset:25408
	ds_read_b64_tr_b16 v[68:69], v209 offset:25440
	v_cvt_pk_bf16_f32 v70, v177, v176
	v_cvt_pk_bf16_f32 v71, v175, v174
	v_cvt_pk_bf16_f32 v72, v171, v170
	v_cvt_pk_bf16_f32 v73, v181, v180
	s_waitcnt lgkmcnt(3)
	s_nop 0
	v_mfma_f32_16x16x32_bf16 v[32:35], v[54:57], v[70:73], v[32:35]
	s_waitcnt lgkmcnt(2)
	v_mfma_f32_16x16x32_bf16 v[36:39], v[58:61], v[70:73], v[36:39]
	s_waitcnt lgkmcnt(1)
	v_mfma_f32_16x16x32_bf16 v[40:43], v[62:65], v[70:73], v[40:43]
	s_waitcnt lgkmcnt(0)
	v_mfma_f32_16x16x32_bf16 v[44:47], v[66:69], v[70:73], v[44:47]
	ds_read_b64_tr_b16 v[54:55], v209 offset:27648
	ds_read_b64_tr_b16 v[58:59], v209 offset:27680
	ds_read_b64_tr_b16 v[62:63], v209 offset:27712
	ds_read_b64_tr_b16 v[66:67], v209 offset:27744
	ds_read_b64_tr_b16 v[56:57], v209 offset:29952
	ds_read_b64_tr_b16 v[60:61], v209 offset:29984
	ds_read_b64_tr_b16 v[64:65], v209 offset:30016
	ds_read_b64_tr_b16 v[68:69], v209 offset:30048
	v_cvt_pk_bf16_f32 v70, v223, v224
	v_cvt_pk_bf16_f32 v71, v225, v226
	v_cvt_pk_bf16_f32 v72, v227, v50
	v_cvt_pk_bf16_f32 v73, v238, v239
	s_waitcnt lgkmcnt(3)
	s_nop 0
	v_mfma_f32_16x16x32_bf16 v[32:35], v[54:57], v[70:73], v[32:35]
	s_waitcnt lgkmcnt(2)
	v_mfma_f32_16x16x32_bf16 v[36:39], v[58:61], v[70:73], v[36:39]
	s_waitcnt lgkmcnt(1)
	v_mfma_f32_16x16x32_bf16 v[54:57], v[62:65], v[70:73], v[40:43]
	s_waitcnt lgkmcnt(0)
	v_mfma_f32_16x16x32_bf16 v[58:61], v[66:69], v[70:73], v[44:47]
	s_nop 0
	ds_read_b64_tr_b16 v[40:41], v209 offset:32256
	ds_read_b64_tr_b16 v[62:63], v209 offset:32288
	ds_read_b64_tr_b16 v[66:67], v209 offset:32320
	ds_read_b64_tr_b16 v[70:71], v209 offset:32352
	ds_read_b64_tr_b16 v[42:43], v209 offset:34560
	ds_read_b64_tr_b16 v[64:65], v209 offset:34592
	ds_read_b64_tr_b16 v[68:69], v209 offset:34624
	ds_read_b64_tr_b16 v[72:73], v209 offset:34656
	v_cvt_pk_bf16_f32 v74, v240, v241
	v_cvt_pk_bf16_f32 v75, v242, v243
	v_cvt_pk_bf16_f32 v76, v244, v48
	v_cvt_pk_bf16_f32 v77, v245, v246
	s_waitcnt lgkmcnt(3)
	s_nop 0
	v_mfma_f32_16x16x32_bf16 v[44:47], v[40:43], v[74:77], v[32:35]
	s_waitcnt lgkmcnt(2)
	v_mfma_f32_16x16x32_bf16 v[40:43], v[62:65], v[74:77], v[36:39]
	s_waitcnt lgkmcnt(1)
	v_mfma_f32_16x16x32_bf16 v[36:39], v[66:69], v[74:77], v[54:57]
	s_waitcnt lgkmcnt(0)
	v_mfma_f32_16x16x32_bf16 v[32:35], v[70:73], v[74:77], v[58:61]
	s_and_saveexec_b64 s[42:43], s[40:41]
	s_cbranch_execz .LBB0_504
; #define LAS __attribute__((address_space(3)))
; template <bool OWN>
; __device__ __forceinline__ void moba_item(const bf16x8 q0, const bf16x8 q1, LAS unsigned char* lds, int lane, int qb, int n, int qid, bool valid, int smax) {
;     ...
;         } else {
;             const float mo = mst[qid], lo_ = lst[qid];
;             f32x4 old[4];
; #pragma unroll
;             for (int c = 0; c < 4; ++c) old[c] = *(LAS f32x4*)(orow + 4 * ((4 * c + g) ^ (qid & 15)));
;             const float mn = fmaxf(mo, mx), ao = __builtin_amdgcn_exp2f(mo - mn), ap = __builtin_amdgcn_exp2f(mx - mn);
; #pragma unroll
;             for (int c = 0; c < 4; ++c) *(LAS f32x4*)(orow + 4 * ((4 * c + g) ^ (qid & 15))) = old[c] * ao + O[c] * ap;
;             if (g == 0) { mst[qid] = mn; lst[qid] = lo_ * ao + sum * ap; }
;         }
	v_lshl_add_u32 v50, v221, 8, 0
	v_mul_lo_u32 v48, v221, s18
	v_add_u32_e32 v54, v50, v48
	ds_read2st64_b32 v[48:49], v54 offset0:4 offset1:8
	v_bitop3_b32 v55, v221, v186, 15 bitop3:0x6c
	v_lshl_add_u32 v72, v55, 4, v50
	v_bitop3_b32 v55, v221, v210, 15 bitop3:0x6c
	v_lshl_add_u32 v73, v55, 4, v50
	v_bitop3_b32 v55, v221, v211, 15 bitop3:0x6c
	v_lshl_add_u32 v74, v55, 4, v50
	v_bitop3_b32 v55, v221, v212, 15 bitop3:0x6c
	v_lshl_add_u32 v75, v55, 4, v50
	s_waitcnt lgkmcnt(0)
	v_max_f32_e32 v50, v48, v48
	v_max_f32_e32 v55, v51, v51
	v_max_f32_e32 v55, v50, v55
	v_sub_f32_e32 v50, v51, v55
	ds_read_b128 v[56:59], v72 offset:24576
	ds_read_b128 v[60:63], v73 offset:24576
	v_sub_f32_e32 v48, v48, v55
	v_exp_f32_e32 v50, v50
	ds_read_b128 v[64:67], v74 offset:24576
	ds_read_b128 v[68:71], v75 offset:24576
	v_exp_f32_e32 v48, v48
	v_pk_mul_f32 v[44:45], v[44:45], v[50:51] op_sel_hi:[1,0]
	v_pk_mul_f32 v[46:47], v[46:47], v[50:51] op_sel_hi:[1,0]
	v_pk_mul_f32 v[40:41], v[40:41], v[50:51] op_sel_hi:[1,0]
	v_pk_mul_f32 v[42:43], v[42:43], v[50:51] op_sel_hi:[1,0]
	v_pk_mul_f32 v[36:37], v[36:37], v[50:51] op_sel_hi:[1,0]
	v_pk_mul_f32 v[38:39], v[38:39], v[50:51] op_sel_hi:[1,0]
	v_pk_mul_f32 v[32:33], v[32:33], v[50:51] op_sel_hi:[1,0]
	v_pk_mul_f32 v[34:35], v[34:35], v[50:51] op_sel_hi:[1,0]
	s_waitcnt lgkmcnt(3)
	v_pk_fma_f32 v[46:47], v[58:59], v[48:49], v[46:47] op_sel_hi:[1,0,1]
	v_pk_fma_f32 v[44:45], v[56:57], v[48:49], v[44:45] op_sel_hi:[1,0,1]
	s_waitcnt lgkmcnt(2)
	v_pk_fma_f32 v[42:43], v[62:63], v[48:49], v[42:43] op_sel_hi:[1,0,1]
	v_pk_fma_f32 v[40:41], v[60:61], v[48:49], v[40:41] op_sel_hi:[1,0,1]
	s_waitcnt lgkmcnt(1)
	v_pk_fma_f32 v[38:39], v[66:67], v[48:49], v[38:39] op_sel_hi:[1,0,1]
	v_pk_fma_f32 v[36:37], v[64:65], v[48:49], v[36:37] op_sel_hi:[1,0,1]
	s_waitcnt lgkmcnt(0)
	v_pk_fma_f32 v[34:35], v[48:49], v[70:71], v[34:35] op_sel_hi:[0,1,1]
	v_pk_fma_f32 v[32:33], v[48:49], v[68:69], v[32:33] op_sel_hi:[0,1,1]
	ds_write_b128 v72, v[44:47] offset:24576
	ds_write_b128 v73, v[40:43] offset:24576
	ds_write_b128 v74, v[36:39] offset:24576
	ds_write_b128 v75, v[32:35] offset:24576
	s_and_b64 exec, exec, s[38:39]
	v_add_f32_e32 v32, v52, v53
	v_mul_f32_e32 v32, v32, v50
	v_fmac_f32_e32 v32, v49, v48
	ds_write2st64_b32 v54, v55, v32 offset0:4 offset1:8
